# XCD-local fast barrier on row-local seams (y->wout, wout->softmax, softmax->crossout, ffn2up->down), verified at runtime
# speedup vs baseline: 1.0172x; 1.0020x over previous
_Z10fwd_kernel4Args:
	s_load_dwordx2 s[12:13], s[0:1], 0x100
	s_add_u32 s74, s0, 0x100
	v_and_b32_e32 v218, 0x3ff, v0
	s_mov_b32 s97, s2
	s_addc_u32 s75, s1, 0
	s_mov_b64 s[4:5], s[0:1]
	v_cmp_eq_u32_e32 vcc, 0, v218
	s_and_saveexec_b64 s[2:3], vcc
	s_cbranch_execz .LBB0_3
	s_add_i32 s8, 0, 0x23fc0
	v_mov_b32_e32 v1, 0
	v_mov_b32_e32 v2, s8
	s_add_i32 s8, 0, 0x23fc4
	s_mov_b64 s[6:7], exec
	ds_write_b32 v2, v1
	v_mov_b32_e32 v2, s8
	ds_write_b32 v2, v1
	v_mbcnt_lo_u32_b32 v1, s6, 0
	v_mbcnt_hi_u32_b32 v1, s7, v1
	v_cmp_eq_u32_e32 vcc, 0, v1
	s_getreg_b32 s8, hwreg(HW_REG_XCC_ID, 0, 4)
	s_and_b64 s[10:11], exec, vcc
	s_mov_b64 exec, s[10:11]
	s_cbranch_execz .LBB0_3
	s_load_dwordx2 s[4:5], s[4:5], 0xf0
	s_lshl_b32 s8, s8, 8
	s_and_b32 s8, s8, 0xf00
	v_mov_b32_e32 v1, 0x10000
	s_waitcnt lgkmcnt(0)
	s_add_u32 s4, s4, s8
	s_addc_u32 s5, s5, 0
	s_bcnt1_i32_b64 s6, s[6:7]
	v_mov_b32_e32 v2, s6
	global_atomic_add v1, v2, s[4:5] offset:1024
	s_lshr_b32 s6, s8, 8
	s_and_b32 s7, s97, 7
	s_cmp_eq_u32 s6, s7
	s_cbranch_scc1 .Lfb_init_ok
	s_sub_u32 s4, s4, s8
	s_subb_u32 s5, s5, 0
	s_add_u32 s4, s4, 0x14000
	s_addc_u32 s5, s5, 0
	v_mov_b32_e32 v1, 0
	v_mov_b32_e32 v2, 1
	s_nop 1
	global_atomic_add v1, v2, s[4:5]
.Lfb_init_ok:
.LBB0_3:
	s_or_b64 exec, exec, s[2:3]
	s_waitcnt lgkmcnt(0)
	v_writelane_b32 v255, s0, 0
	s_mov_b64 s[10:11], s[0:1]
	s_barrier
	s_load_dwordx2 s[8:9], s[10:11], 0xf0
	s_mov_b32 s30, s12
	s_mov_b32 s31, s97
	v_mov_b32_e32 v2, v218
	s_lshl_b32 s34, s30, 3
	v_readfirstlane_b32 s2, v2
	s_ashr_i32 s33, s2, 6
	s_lshl_b32 s2, s31, 3
	s_add_i32 s35, s33, s2
	s_waitcnt lgkmcnt(0)
	s_add_u32 s36, s8, 0x100000
	v_and_b32_e32 v1, 63, v2
	s_addc_u32 s37, s9, 0
	v_writelane_b32 v255, s1, 1
	s_cmpk_gt_i32 s35, 0x6dff
	v_lshlrev_b32_e32 v50, 3, v1
	s_cbranch_scc1 .LBB0_69
	s_lshl_b32 s2, s33, 14
	v_lshrrev_b32_e32 v40, 5, v1
	v_and_b32_e32 v2, 31, v2
	s_add_i32 s2, s2, 0
	v_lshlrev_b32_e32 v4, 2, v2
	v_mul_u32_u24_e32 v5, 0x84, v40
	v_add3_u32 v41, s2, v4, v5
	v_lshrrev_b32_e32 v42, 3, v1
	v_and_b32_e32 v4, 56, v50
	v_mul_u32_u24_e32 v5, 0x84, v4
	v_lshlrev_b32_e32 v6, 2, v42
	v_add3_u32 v43, s2, v5, v6
	s_lshl_b32 s2, s35, 1
	v_mov_b32_e32 v3, 0
	v_or_b32_e32 v44, 8, v42
	v_or_b32_e32 v45, 16, v42
	v_or_b32_e32 v46, 24, v42
	s_lshl_b32 s38, s35, 5
	s_lshl_b32 s39, s34, 5
	s_add_i32 s40, s2, 0x1ea00
	s_lshl_b32 s41, s34, 1
	s_movk_i32 s42, 0x2000
	s_movk_i32 s43, 0x4000
	s_movk_i32 s44, 0x6000
	s_mov_b32 s45, 0x8000
	s_mov_b32 s46, 0xa000
	s_mov_b32 s47, 0xc000
	s_mov_b32 s48, 0xe000
	s_mov_b32 s49, 0x10000
	s_mov_b32 s50, 0x12000
	s_mov_b32 s51, 0x14000
	s_mov_b32 s52, 0x16000
	s_mov_b32 s53, 0x18000
	s_mov_b32 s54, 0x1a000
	s_mov_b32 s55, 0x1c000
	s_mov_b32 s56, 0x1e000
	s_mov_b32 s57, 0x20000
	s_mov_b32 s58, 0x22000
	s_mov_b32 s59, 0x24000
	s_mov_b32 s60, 0x26000
	s_mov_b32 s61, 0x28000
	s_mov_b32 s62, 0x2a000
	s_mov_b32 s63, 0x2c000
	s_mov_b32 s64, 0x2e000
	s_mov_b32 s65, 0x30000
	s_mov_b32 s66, 0x32000
	s_mov_b32 s67, 0x34000
	s_mov_b32 s68, 0x36000
	s_mov_b32 s69, 0x38000
	s_mov_b32 s70, 0x3a000
	s_mov_b32 s71, 0x3c000
	s_mov_b32 s72, 0x3e000
	s_movk_i32 s73, 0x2c00
	s_mov_b64 s[2:3], 0x2680000
	s_mov_b32 s0, 0x40000
	s_mov_b32 s1, 0x44000
	s_mov_b32 s76, 0x48000
	s_mov_b32 s77, 0x4c000
	s_mov_b32 s78, 0x50000
	s_mov_b32 s79, 0x54000
	s_mov_b32 s80, 0x58000
	s_mov_b32 s81, 0x5c000
	s_mov_b32 s82, 0x60000
	s_mov_b32 s83, 0x64000
	s_mov_b32 s84, 0x68000
	s_mov_b32 s85, 0x6c000
	s_mov_b32 s86, 0x70000
	s_mov_b32 s87, 0x74000
	s_mov_b32 s88, 0x78000
	s_mov_b32 s89, 0x7c000
	s_mov_b64 s[12:13], 0x2080000
	s_mov_b64 s[14:15], 0x1c80000
	s_mov_b64 s[16:17], 0x1a80600
	s_mov_b64 s[18:19], 0x1a80200
	s_mov_b64 s[20:21], 0x1a80000
	s_movk_i32 s90, 0x5000
	s_mov_b64 s[22:23], 0x1080000
	s_mov_b64 s[24:25], 0xb00000
	v_lshlrev_b32_e32 v2, 2, v2
	v_add_u32_e32 v47, 0x400, v41
	v_add_u32_e32 v48, 0x800, v41
	v_add_u32_e32 v49, 0xc00, v41
	v_add_u32_e32 v51, 0x1000, v41
	v_add_u32_e32 v52, 0x1400, v41
	v_add_u32_e32 v53, 0x1800, v41
	v_add_u32_e32 v54, 0x1c00, v41
	v_lshlrev_b32_e32 v4, 1, v4
	v_mov_b32_e32 v55, 0x100
	s_mov_b32 s91, s35
	s_branch .LBB0_7

.LBB0_99:
	s_or_b64 exec, exec, s[2:3]
	s_barrier
	v_readlane_b32 s0, v255, 0
	v_readlane_b32 s1, v255, 1
	s_nop 4
	s_load_dword s2, s[0:1], 0x100
	s_load_dwordx2 s[4:5], s[0:1], 0xf0
	s_getreg_b32 s3, hwreg(HW_REG_XCC_ID, 0, 4)
	s_and_b32 s3, s3, 15
	s_lshl_b32 s3, s3, 8
	s_waitcnt lgkmcnt(0)
	s_add_u32 s4, s4, 0x14000
	s_addc_u32 s5, s5, 0
	v_mov_b32_e32 v2, 0
	global_load_dword v3, v2, s[4:5] sc1
	s_waitcnt vmcnt(0)
	v_readfirstlane_b32 s0, v3
	s_add_u32 s4, s4, s3
	s_addc_u32 s5, s5, 0
	s_add_u32 s4, s4, 0x100
	s_addc_u32 s5, s5, 0
	s_cmp_eq_u32 s0, 0
	s_cselect_b32 s1, 32, 0
	s_cmpk_eq_u32 s2, 0x100
	s_cselect_b32 s1, s1, 0
	v_writelane_b32 v255, s1, 40
	v_writelane_b32 v255, s4, 41
	v_writelane_b32 v255, s5, 42
	s_load_dword s0, s[78:79], 0x108
	s_add_i32 s2, 0, 0x1c800
	v_writelane_b32 v255, s2, 2
	s_add_i32 s2, 0, 0x1e020
	v_writelane_b32 v255, s2, 3
	s_add_i32 s2, 0, 0x1e820
	v_writelane_b32 v255, s2, 4
	s_add_i32 s2, 0, 0x1e3a0
	s_mul_i32 s1, s77, s76
	v_writelane_b32 v255, s2, 5
	s_waitcnt lgkmcnt(0)
	s_mul_i32 s77, s1, s0
	v_writelane_b32 v255, s97, 6
	s_add_i32 s84, 0, 0x23fc0
	v_writelane_b32 v255, s77, 7
	s_add_i32 s85, 0, 0x23fc4
	v_writelane_b32 v255, s84, 8
	s_mov_b32 s81, 0
	s_mov_b64 s[12:13], -1
	s_movk_i32 s68, 0xb00
	s_movk_i32 s0, 0x2000
	s_mov_b32 s69, 0x1fffe0
	s_movk_i32 s70, 0x161
	s_mov_b32 s71, 0x10000
	v_mov_b32_e32 v0, 0
	s_mov_b64 s[72:73], 0x40000
	s_movk_i32 s1, 0x3c0
	s_mov_b32 s74, 0x18000
	s_mov_b64 s[94:95], 0x80
	s_mov_b32 s75, 0x8000
	s_movk_i32 s82, 0x80
	v_mov_b32_e32 v219, 0x358637bd
	s_mov_b32 s86, 0x800000
	s_movk_i32 s83, 0x1600
	s_mov_b64 s[90:91], 0x10000
	v_mov_b32_e32 v254, 0x2000
	v_mov_b32_e32 v225, 0x13000
	v_mov_b32_e32 v253, 1
	s_mov_b32 s87, 0x40000
	s_mov_b32 s92, 0x48000
	s_mov_b32 s93, 0x50000
	s_movk_i32 s33, 0x1000
	s_movk_i32 s88, 0x3000
	s_movk_i32 s89, 0x101
	v_mov_b32_e32 v224, 0x260
	v_mov_b64_e32 v[200:201], 0x200
	v_mov_b64_e32 v[202:203], 0x1ff
	v_mov_b32_e32 v226, 0x80
	v_mov_b32_e32 v227, 0xfe0
	s_mov_b32 s6, 0
	s_mov_b32 s96, 0x3e38aa3b
	v_writelane_b32 v255, s85, 9
	s_branch .LBB0_102

.LBB0_818:
	s_waitcnt vmcnt(0)
	v_mov_b32_e32 v1, v218
	s_waitcnt lgkmcnt(0)
	s_barrier
	s_nop 0
	v_cmp_eq_u32_e32 vcc, 0, v1
	s_and_saveexec_b64 s[2:3], vcc
	s_xor_b64 s[2:3], exec, s[2:3]
	s_cbranch_execz .LBB0_871
	v_readlane_b32 s100, v255, 40
	s_nop 3
	s_cmp_eq_u32 s100, 0
	s_cbranch_scc1 .Lfb_slow_5
	v_readlane_b32 s100, v255, 41
	v_readlane_b32 s101, v255, 42
	v_mov_b32_e32 v2, 0
	v_mov_b32_e32 v3, 1
	v_mov_b32_e32 v4, 1
	s_nop 2
	global_atomic_add v3, v2, v3, s[100:101] sc0
	s_waitcnt vmcnt(0)
	v_readfirstlane_b32 vcc_hi, v3
	s_nop 3
	s_lshr_b32 vcc_lo, vcc_hi, 5
	s_add_i32 vcc_hi, vcc_hi, 1
	s_and_b32 vcc_hi, vcc_hi, 31
	s_cmp_lg_u32 vcc_hi, 0
	s_cbranch_scc1 .Lfb_spin_5
	global_atomic_add v2, v4, s[100:101] offset:128
	s_branch .Lfb_done_5
.Lfb_spin_5:
	s_sleep 1
	global_load_dword v3, v2, s[100:101] offset:128 sc1
	s_waitcnt vmcnt(0)
	v_readfirstlane_b32 vcc_hi, v3
	s_nop 3
	s_cmp_eq_u32 vcc_hi, vcc_lo
	s_cbranch_scc1 .Lfb_spin_5
.Lfb_done_5:
	buffer_inv sc1
	s_waitcnt vmcnt(0)
	s_branch .LBB0_871
.Lfb_slow_5:
	v_mov_b32_e32 v1, s84
	s_getreg_b32 s4, hwreg(HW_REG_XCC_ID, 0, 4)
	s_waitcnt vmcnt(0) expcnt(0) lgkmcnt(0)
	ds_read_b32 v3, v1
	v_mov_b32_e32 v1, s85
	ds_read_b32 v2, v1
	s_and_b32 s48, s4, 15
	s_waitcnt lgkmcnt(1)
	v_cmp_ne_u32_e32 vcc, 0, v3
	s_cbranch_vccnz .LBB0_834
	s_add_u32 s4, s6, 0x10200
	s_addc_u32 s5, s7, 0
	s_add_u32 s8, s6, 0x10400
	s_addc_u32 s9, s7, 0
	s_add_u32 s10, s6, 0x10500
	s_addc_u32 s11, s7, 0
	s_add_u32 s12, s6, 0x10600
	s_addc_u32 s13, s7, 0
	s_add_u32 s14, s6, 0x10700
	s_addc_u32 s15, s7, 0
	s_add_u32 s16, s6, 0x10800
	s_addc_u32 s17, s7, 0
	s_add_u32 s18, s6, 0x10900
	s_addc_u32 s19, s7, 0
	s_add_u32 s20, s6, 0x10a00
	s_addc_u32 s21, s7, 0
	s_add_u32 s22, s6, 0x10b00
	s_addc_u32 s23, s7, 0
	s_add_u32 s24, s6, 0x10c00
	s_addc_u32 s25, s7, 0
	s_add_u32 s26, s6, 0x10d00
	s_addc_u32 s27, s7, 0
	s_add_u32 s28, s6, 0x10e00
	s_addc_u32 s29, s7, 0
	s_add_u32 s30, s6, 0x10f00
	s_addc_u32 s31, s7, 0
	s_add_u32 s34, s6, 0x11000
	s_addc_u32 s35, s7, 0
	s_add_u32 s36, s6, 0x11100
	s_addc_u32 s37, s7, 0
	s_add_u32 s38, s6, 0x11200
	s_addc_u32 s39, s7, 0
	s_add_u32 s40, s6, 0x11300
	s_addc_u32 s41, s7, 0
	s_mov_b32 s49, 1
	s_branch .LBB0_822

.LBB0_913:
	s_waitcnt vmcnt(0)
	v_mov_b32_e32 v1, v218
	s_waitcnt lgkmcnt(0)
	s_barrier
	s_nop 0
	v_cmp_eq_u32_e32 vcc, 0, v1
	s_and_saveexec_b64 s[2:3], vcc
	s_cbranch_execz .LBB0_965
	v_readlane_b32 s100, v255, 40
	s_nop 3
	s_cmp_eq_u32 s100, 0
	s_cbranch_scc1 .Lfb_slow_6
	v_readlane_b32 s100, v255, 41
	v_readlane_b32 s101, v255, 42
	v_mov_b32_e32 v2, 0
	v_mov_b32_e32 v3, 1
	v_mov_b32_e32 v4, 1
	s_nop 2
	global_atomic_add v3, v2, v3, s[100:101] sc0
	s_waitcnt vmcnt(0)
	v_readfirstlane_b32 vcc_hi, v3
	s_nop 3
	s_lshr_b32 vcc_lo, vcc_hi, 5
	s_add_i32 vcc_hi, vcc_hi, 1
	s_and_b32 vcc_hi, vcc_hi, 31
	s_cmp_lg_u32 vcc_hi, 0
	s_cbranch_scc1 .Lfb_spin_6
	global_atomic_add v2, v4, s[100:101] offset:128
	s_branch .Lfb_done_6

.Lfb_slow_6:
	v_mov_b32_e32 v1, s84
	s_getreg_b32 s6, hwreg(HW_REG_XCC_ID, 0, 4)
	s_waitcnt vmcnt(0) expcnt(0) lgkmcnt(0)
	ds_read_b32 v3, v1
	v_mov_b32_e32 v1, s85
	ds_read_b32 v2, v1
	s_and_b32 s48, s6, 15
	s_waitcnt lgkmcnt(1)
	v_cmp_ne_u32_e32 vcc, 0, v3
	s_cbranch_vccnz .LBB0_929
	s_add_u32 s6, s4, 0x10200
	s_addc_u32 s7, s5, 0
	s_add_u32 s8, s4, 0x10400
	s_addc_u32 s9, s5, 0
	s_add_u32 s10, s4, 0x10500
	s_addc_u32 s11, s5, 0
	s_add_u32 s12, s4, 0x10600
	s_addc_u32 s13, s5, 0
	s_add_u32 s14, s4, 0x10700
	s_addc_u32 s15, s5, 0
	s_add_u32 s16, s4, 0x10800
	s_addc_u32 s17, s5, 0
	s_add_u32 s18, s4, 0x10900
	s_addc_u32 s19, s5, 0
	s_add_u32 s20, s4, 0x10a00
	s_addc_u32 s21, s5, 0
	s_add_u32 s22, s4, 0x10b00
	s_addc_u32 s23, s5, 0
	s_add_u32 s24, s4, 0x10c00
	s_addc_u32 s25, s5, 0
	s_add_u32 s26, s4, 0x10d00
	s_addc_u32 s27, s5, 0
	s_add_u32 s28, s4, 0x10e00
	s_addc_u32 s29, s5, 0
	s_add_u32 s30, s4, 0x10f00
	s_addc_u32 s31, s5, 0
	s_add_u32 s34, s4, 0x11000
	s_addc_u32 s35, s5, 0
	s_add_u32 s36, s4, 0x11100
	s_addc_u32 s37, s5, 0
	s_add_u32 s38, s4, 0x11200
	s_addc_u32 s39, s5, 0
	s_add_u32 s40, s4, 0x11300
	s_addc_u32 s41, s5, 0
	s_mov_b32 s49, 1
	s_branch .LBB0_917

.Lfb_slow_7:
	v_mov_b32_e32 v1, s84
	s_getreg_b32 s4, hwreg(HW_REG_XCC_ID, 0, 4)
	s_waitcnt vmcnt(0) expcnt(0) lgkmcnt(0)
	ds_read_b32 v3, v1
	v_mov_b32_e32 v1, s85
	ds_read_b32 v2, v1
	s_and_b32 s49, s4, 15
	s_waitcnt lgkmcnt(1)
	v_cmp_ne_u32_e32 vcc, 0, v3
	s_cbranch_vccnz .LBB0_1039
	s_add_u32 s4, s6, 0x10200
	s_addc_u32 s5, s7, 0
	s_add_u32 s8, s6, 0x10400
	s_addc_u32 s9, s7, 0
	s_add_u32 s10, s6, 0x10500
	s_addc_u32 s11, s7, 0
	s_add_u32 s12, s6, 0x10600
	s_addc_u32 s13, s7, 0
	s_add_u32 s14, s6, 0x10700
	s_addc_u32 s15, s7, 0
	s_add_u32 s16, s6, 0x10800
	s_addc_u32 s17, s7, 0
	s_add_u32 s18, s6, 0x10900
	s_addc_u32 s19, s7, 0
	s_add_u32 s20, s6, 0x10a00
	s_addc_u32 s21, s7, 0
	s_add_u32 s22, s6, 0x10b00
	s_addc_u32 s23, s7, 0
	s_add_u32 s24, s6, 0x10c00
	s_addc_u32 s25, s7, 0
	s_add_u32 s26, s6, 0x10d00
	s_addc_u32 s27, s7, 0
	s_add_u32 s28, s6, 0x10e00
	s_addc_u32 s29, s7, 0
	s_add_u32 s30, s6, 0x10f00
	s_addc_u32 s31, s7, 0
	s_add_u32 s34, s6, 0x11000
	s_addc_u32 s35, s7, 0
	s_add_u32 s36, s6, 0x11100
	s_addc_u32 s37, s7, 0
	s_add_u32 s38, s6, 0x11200
	s_addc_u32 s39, s7, 0
	s_add_u32 s40, s6, 0x11300
	s_addc_u32 s41, s7, 0
	s_mov_b32 s50, 1
	s_branch .LBB0_1027

	.amdhsa_kernel _Z10fwd_kernel4Args
		.amdhsa_group_segment_fixed_size 0
		.amdhsa_private_segment_fixed_size 0
		.amdhsa_kernarg_size 512
		.amdhsa_user_sgpr_count 2
		.amdhsa_user_sgpr_dispatch_ptr 0
		.amdhsa_user_sgpr_queue_ptr 0
		.amdhsa_user_sgpr_kernarg_segment_ptr 1
		.amdhsa_user_sgpr_dispatch_id 0
		.amdhsa_user_sgpr_kernarg_preload_length 0
		.amdhsa_user_sgpr_kernarg_preload_offset 0
		.amdhsa_user_sgpr_private_segment_size 0
		.amdhsa_uses_dynamic_stack 0
		.amdhsa_enable_private_segment 0
		.amdhsa_system_sgpr_workgroup_id_x 1
		.amdhsa_system_sgpr_workgroup_id_y 0
		.amdhsa_system_sgpr_workgroup_id_z 0
		.amdhsa_system_sgpr_workgroup_info 0
		.amdhsa_system_vgpr_workitem_id 2
		.amdhsa_next_free_vgpr 256
		.amdhsa_next_free_sgpr 102
		.amdhsa_accum_offset 256
		.amdhsa_reserve_vcc 1
		.amdhsa_float_round_mode_32 0
		.amdhsa_float_round_mode_16_64 0
		.amdhsa_float_denorm_mode_32 3
		.amdhsa_float_denorm_mode_16_64 3
		.amdhsa_dx10_clamp 1
		.amdhsa_ieee_mode 1
		.amdhsa_fp16_overflow 0
		.amdhsa_tg_split 0
		.amdhsa_exception_fp_ieee_invalid_op 0
		.amdhsa_exception_fp_denorm_src 0
		.amdhsa_exception_fp_ieee_div_zero 0
		.amdhsa_exception_fp_ieee_overflow 0
		.amdhsa_exception_fp_ieee_underflow 0
		.amdhsa_exception_fp_ieee_inexact 0
		.amdhsa_exception_int_div_zero 0
	.end_amdhsa_kernel

amdhsa.kernels:
  - .agpr_count:     0
    .args:
      - .offset:         0
        .size:           256
        .value_kind:     by_value
      - .offset:         256
        .size:           4
        .value_kind:     hidden_block_count_x
      - .offset:         260
        .size:           4
        .value_kind:     hidden_block_count_y
      - .offset:         264
        .size:           4
        .value_kind:     hidden_block_count_z
      - .offset:         268
        .size:           2
        .value_kind:     hidden_group_size_x
      - .offset:         270
        .size:           2
        .value_kind:     hidden_group_size_y
      - .offset:         272
        .size:           2
        .value_kind:     hidden_group_size_z
      - .offset:         274
        .size:           2
        .value_kind:     hidden_remainder_x
      - .offset:         276
        .size:           2
        .value_kind:     hidden_remainder_y
      - .offset:         278
        .size:           2
        .value_kind:     hidden_remainder_z
      - .offset:         296
        .size:           8
        .value_kind:     hidden_global_offset_x
      - .offset:         304
        .size:           8
        .value_kind:     hidden_global_offset_y
      - .offset:         312
        .size:           8
        .value_kind:     hidden_global_offset_z
      - .offset:         320
        .size:           2
        .value_kind:     hidden_grid_dims
      - .offset:         344
        .size:           8
        .value_kind:     hidden_multigrid_sync_arg
      - .offset:         376
        .size:           4
        .value_kind:     hidden_dynamic_lds_size
    .group_segment_fixed_size: 0
    .kernarg_segment_align: 8
    .kernarg_segment_size: 512
    .language:       OpenCL C
    .language_version:
      - 2
      - 0
    .max_flat_workgroup_size: 512
    .name:           _Z10fwd_kernel4Args
    .private_segment_fixed_size: 0
    .sgpr_count:     108
    .sgpr_spill_count: 21
    .symbol:         _Z10fwd_kernel4Args.kd
    .uniform_work_group_size: 1
    .uses_dynamic_stack: false
    .vgpr_count:     256
    .vgpr_spill_count: 0
    .wavefront_size: 64
